# P0 adaLN partial sums: the 32 weight loads of an item issued as one batch before the conditioning values are fetched (was a window of 8 in flight), multiply-add chain in source order
# baseline (speedup 1.0000x reference)
.LBB0_22:
	s_and_b32 s5, s4, 15
	s_lshl_b32 s33, s5, 6
	v_mov_b32_e32 v218, s58
	v_and_b32_e32 v218, 0xffffff00, v218
	v_or_b32_e32 v218, v218, v12
	v_ashrrev_i32_e32 v219, 31, v218
	v_add_u32_e32 v222, s33, v13
	v_mad_i64_i32 v[220:221], s[54:55], v222, s80, v[6:7]
	v_lshl_add_u64 v[220:221], v[218:219], 2, v[220:221]
	s_mov_b32 vcc_hi, 0
	global_load_dword v184, v[220:221], off nt
	s_mov_b32 vcc_lo, 0x3000
	v_lshl_add_u64 v[222:223], v[220:221], 0, vcc
	global_load_dword v185, v[222:223], off nt
	s_mov_b32 vcc_lo, 0x6000
	v_lshl_add_u64 v[222:223], v[220:221], 0, vcc
	global_load_dword v186, v[222:223], off nt
	s_mov_b32 vcc_lo, 0x9000
	v_lshl_add_u64 v[222:223], v[220:221], 0, vcc
	global_load_dword v187, v[222:223], off nt
	s_mov_b32 vcc_lo, 0xc000
	v_lshl_add_u64 v[222:223], v[220:221], 0, vcc
	global_load_dword v188, v[222:223], off nt
	s_mov_b32 vcc_lo, 0xf000
	v_lshl_add_u64 v[222:223], v[220:221], 0, vcc
	global_load_dword v189, v[222:223], off nt
	s_mov_b32 vcc_lo, 0x12000
	v_lshl_add_u64 v[222:223], v[220:221], 0, vcc
	global_load_dword v190, v[222:223], off nt
	s_mov_b32 vcc_lo, 0x15000
	v_lshl_add_u64 v[222:223], v[220:221], 0, vcc
	global_load_dword v191, v[222:223], off nt
	s_mov_b32 vcc_lo, 0x18000
	v_lshl_add_u64 v[222:223], v[220:221], 0, vcc
	global_load_dword v192, v[222:223], off nt
	s_mov_b32 vcc_lo, 0x1b000
	v_lshl_add_u64 v[222:223], v[220:221], 0, vcc
	global_load_dword v193, v[222:223], off nt
	s_mov_b32 vcc_lo, 0x1e000
	v_lshl_add_u64 v[222:223], v[220:221], 0, vcc
	global_load_dword v194, v[222:223], off nt
	s_mov_b32 vcc_lo, 0x21000
	v_lshl_add_u64 v[222:223], v[220:221], 0, vcc
	global_load_dword v195, v[222:223], off nt
	s_mov_b32 vcc_lo, 0x24000
	v_lshl_add_u64 v[222:223], v[220:221], 0, vcc
	global_load_dword v196, v[222:223], off nt
	s_mov_b32 vcc_lo, 0x27000
	v_lshl_add_u64 v[222:223], v[220:221], 0, vcc
	global_load_dword v197, v[222:223], off nt
	s_mov_b32 vcc_lo, 0x2a000
	v_lshl_add_u64 v[222:223], v[220:221], 0, vcc
	global_load_dword v198, v[222:223], off nt
	s_mov_b32 vcc_lo, 0x2d000
	v_lshl_add_u64 v[222:223], v[220:221], 0, vcc
	global_load_dword v199, v[222:223], off nt
	s_mov_b32 vcc_lo, 0x30000
	v_lshl_add_u64 v[222:223], v[220:221], 0, vcc
	global_load_dword v200, v[222:223], off nt
	s_mov_b32 vcc_lo, 0x33000
	v_lshl_add_u64 v[222:223], v[220:221], 0, vcc
	global_load_dword v201, v[222:223], off nt
	s_mov_b32 vcc_lo, 0x36000
	v_lshl_add_u64 v[222:223], v[220:221], 0, vcc
	global_load_dword v202, v[222:223], off nt
	s_mov_b32 vcc_lo, 0x39000
	v_lshl_add_u64 v[222:223], v[220:221], 0, vcc
	global_load_dword v203, v[222:223], off nt
	s_mov_b32 vcc_lo, 0x3c000
	v_lshl_add_u64 v[222:223], v[220:221], 0, vcc
	global_load_dword v204, v[222:223], off nt
	s_mov_b32 vcc_lo, 0x3f000
	v_lshl_add_u64 v[222:223], v[220:221], 0, vcc
	global_load_dword v205, v[222:223], off nt
	s_mov_b32 vcc_lo, 0x42000
	v_lshl_add_u64 v[222:223], v[220:221], 0, vcc
	global_load_dword v206, v[222:223], off nt
	s_mov_b32 vcc_lo, 0x45000
	v_lshl_add_u64 v[222:223], v[220:221], 0, vcc
	global_load_dword v207, v[222:223], off nt
	s_mov_b32 vcc_lo, 0x48000
	v_lshl_add_u64 v[222:223], v[220:221], 0, vcc
	global_load_dword v208, v[222:223], off nt
	s_mov_b32 vcc_lo, 0x4b000
	v_lshl_add_u64 v[222:223], v[220:221], 0, vcc
	global_load_dword v209, v[222:223], off nt
	s_mov_b32 vcc_lo, 0x4e000
	v_lshl_add_u64 v[222:223], v[220:221], 0, vcc
	global_load_dword v210, v[222:223], off nt
	s_mov_b32 vcc_lo, 0x51000
	v_lshl_add_u64 v[222:223], v[220:221], 0, vcc
	global_load_dword v211, v[222:223], off nt
	s_mov_b32 vcc_lo, 0x54000
	v_lshl_add_u64 v[222:223], v[220:221], 0, vcc
	global_load_dword v212, v[222:223], off nt
	s_mov_b32 vcc_lo, 0x57000
	v_lshl_add_u64 v[222:223], v[220:221], 0, vcc
	global_load_dword v213, v[222:223], off nt
	s_mov_b32 vcc_lo, 0x5a000
	v_lshl_add_u64 v[222:223], v[220:221], 0, vcc
	global_load_dword v214, v[222:223], off nt
	s_mov_b32 vcc_lo, 0x5d000
	v_lshl_add_u64 v[222:223], v[220:221], 0, vcc
	global_load_dword v215, v[222:223], off nt
	v_or_b32_e32 v4, s33, v21
	v_lshlrev_b32_e32 v4, 2, v4
	v_lshl_add_u64 v[8:9], v[0:1], 0, v[4:5]
	s_barrier
	global_load_dword v8, v[8:9], off
	s_and_saveexec_b64 s[54:55], s[10:11]
	s_cbranch_execz .LBB0_24
	v_or_b32_e32 v4, s33, v20
	v_lshlrev_b32_e32 v4, 2, v4
	v_lshl_add_u64 v[10:11], v[2:3], 0, v[4:5]
	global_load_dword v4, v[10:11], off
	s_waitcnt vmcnt(0)
	v_mul_f32_e32 v9, 0xbfb8aa3b, v4
	v_exp_f32_e32 v9, v9
	s_nop 0
	v_add_f32_e32 v9, 1.0, v9
	v_div_scale_f32 v10, vcc, v9, v9, v4
	v_rcp_f32_e32 v11, v10
	v_div_scale_f32 v27, vcc, v4, v9, v4
	v_fma_f32 v28, -v10, v11, 1.0
	v_fmac_f32_e32 v11, v28, v11
	v_mul_f32_e32 v28, v27, v11
	v_fma_f32 v29, -v10, v28, v27
	v_fmac_f32_e32 v28, v29, v11
	v_fma_f32 v10, -v10, v28, v27
	v_div_fmas_f32 v10, v10, v11, v28
	v_div_fixup_f32 v4, v10, v9, v4
	ds_write_b32 v22, v4

.LBB0_26:
	s_or_b64 exec, exec, s[54:55]
	s_and_b32 s54, s58, 0xffffff00
	s_waitcnt vmcnt(0)
	v_or_b32_e32 v8, s54, v12
	v_add_u32_e32 v4, s33, v13
	v_mad_i64_i32 v[10:11], s[54:55], v4, s80, v[6:7]
	v_ashrrev_i32_e32 v9, 31, v8
	v_lshl_add_u64 v[10:11], v[8:9], 2, v[10:11]
	v_add_co_u32_e32 v28, vcc, s80, v10
	s_movk_i32 s33, 0x6000
	s_nop 0
	v_addc_co_u32_e32 v29, vcc, 0, v11, vcc
	s_waitcnt lgkmcnt(0)
	s_barrier
	v_mov_b32_e32 v34, 0
	v_mov_b32_e32 v33, 0
	v_mov_b32_e32 v32, 0
	v_mov_b32_e32 v31, 0
	v_mov_b32_e32 v30, 0
	v_mov_b32_e32 v29, 0
	v_mov_b32_e32 v28, 0
	v_mov_b32_e32 v27, 0
	v_mov_b32_e32 v4, 0
	ds_read_b128 v[36:39], v24 offset:0
	ds_read_b128 v[40:43], v24 offset:16
	ds_read_b32 v68, v24 offset:32
	ds_read_b128 v[44:47], v24 offset:48
	ds_read_b128 v[48:51], v24 offset:64
	ds_read_b32 v69, v24 offset:80
	ds_read_b128 v[52:55], v24 offset:96
	ds_read_b128 v[56:59], v24 offset:112
	ds_read_b32 v70, v24 offset:128
	ds_read_b128 v[60:63], v24 offset:144
	ds_read_b128 v[64:67], v24 offset:160
	ds_read_b32 v71, v24 offset:176
	s_waitcnt vmcnt(28) lgkmcnt(0)
	v_fmac_f32_e32 v34, v184, v36
	v_fmac_f32_e32 v33, v184, v37
	v_fmac_f32_e32 v32, v184, v38
	v_fmac_f32_e32 v31, v184, v39
	v_fmac_f32_e32 v30, v184, v40
	v_fmac_f32_e32 v29, v184, v41
	v_fmac_f32_e32 v28, v184, v42
	v_fmac_f32_e32 v27, v184, v43
	v_fmac_f32_e32 v4, v184, v68
	v_fmac_f32_e32 v34, v185, v44
	v_fmac_f32_e32 v33, v185, v45
	v_fmac_f32_e32 v32, v185, v46
	v_fmac_f32_e32 v31, v185, v47
	v_fmac_f32_e32 v30, v185, v48
	v_fmac_f32_e32 v29, v185, v49
	v_fmac_f32_e32 v28, v185, v50
	v_fmac_f32_e32 v27, v185, v51
	v_fmac_f32_e32 v4, v185, v69
	v_fmac_f32_e32 v34, v186, v52
	v_fmac_f32_e32 v33, v186, v53
	v_fmac_f32_e32 v32, v186, v54
	v_fmac_f32_e32 v31, v186, v55
	v_fmac_f32_e32 v30, v186, v56
	v_fmac_f32_e32 v29, v186, v57
	v_fmac_f32_e32 v28, v186, v58
	v_fmac_f32_e32 v27, v186, v59
	v_fmac_f32_e32 v4, v186, v70
	v_fmac_f32_e32 v34, v187, v60
	v_fmac_f32_e32 v33, v187, v61
	v_fmac_f32_e32 v32, v187, v62
	v_fmac_f32_e32 v31, v187, v63
	v_fmac_f32_e32 v30, v187, v64
	v_fmac_f32_e32 v29, v187, v65
	v_fmac_f32_e32 v28, v187, v66
	v_fmac_f32_e32 v27, v187, v67
	v_fmac_f32_e32 v4, v187, v71
	ds_read_b128 v[36:39], v24 offset:192
	ds_read_b128 v[40:43], v24 offset:208
	ds_read_b32 v68, v24 offset:224
	ds_read_b128 v[44:47], v24 offset:240
	ds_read_b128 v[48:51], v24 offset:256
	ds_read_b32 v69, v24 offset:272
	ds_read_b128 v[52:55], v24 offset:288
	ds_read_b128 v[56:59], v24 offset:304
	ds_read_b32 v70, v24 offset:320
	ds_read_b128 v[60:63], v24 offset:336
	ds_read_b128 v[64:67], v24 offset:352
	ds_read_b32 v71, v24 offset:368
	s_waitcnt vmcnt(24) lgkmcnt(0)
	v_fmac_f32_e32 v34, v188, v36
	v_fmac_f32_e32 v33, v188, v37
	v_fmac_f32_e32 v32, v188, v38
	v_fmac_f32_e32 v31, v188, v39
	v_fmac_f32_e32 v30, v188, v40
	v_fmac_f32_e32 v29, v188, v41
	v_fmac_f32_e32 v28, v188, v42
	v_fmac_f32_e32 v27, v188, v43
	v_fmac_f32_e32 v4, v188, v68
	v_fmac_f32_e32 v34, v189, v44
	v_fmac_f32_e32 v33, v189, v45
	v_fmac_f32_e32 v32, v189, v46
	v_fmac_f32_e32 v31, v189, v47
	v_fmac_f32_e32 v30, v189, v48
	v_fmac_f32_e32 v29, v189, v49
	v_fmac_f32_e32 v28, v189, v50
	v_fmac_f32_e32 v27, v189, v51
	v_fmac_f32_e32 v4, v189, v69
	v_fmac_f32_e32 v34, v190, v52
	v_fmac_f32_e32 v33, v190, v53
	v_fmac_f32_e32 v32, v190, v54
	v_fmac_f32_e32 v31, v190, v55
	v_fmac_f32_e32 v30, v190, v56
	v_fmac_f32_e32 v29, v190, v57
	v_fmac_f32_e32 v28, v190, v58
	v_fmac_f32_e32 v27, v190, v59
	v_fmac_f32_e32 v4, v190, v70
	v_fmac_f32_e32 v34, v191, v60
	v_fmac_f32_e32 v33, v191, v61
	v_fmac_f32_e32 v32, v191, v62
	v_fmac_f32_e32 v31, v191, v63
	v_fmac_f32_e32 v30, v191, v64
	v_fmac_f32_e32 v29, v191, v65
	v_fmac_f32_e32 v28, v191, v66
	v_fmac_f32_e32 v27, v191, v67
	v_fmac_f32_e32 v4, v191, v71
	ds_read_b128 v[36:39], v24 offset:384
	ds_read_b128 v[40:43], v24 offset:400
	ds_read_b32 v68, v24 offset:416
	ds_read_b128 v[44:47], v24 offset:432
	ds_read_b128 v[48:51], v24 offset:448
	ds_read_b32 v69, v24 offset:464
	ds_read_b128 v[52:55], v24 offset:480
	ds_read_b128 v[56:59], v24 offset:496
	ds_read_b32 v70, v24 offset:512
	ds_read_b128 v[60:63], v24 offset:528
	ds_read_b128 v[64:67], v24 offset:544
	ds_read_b32 v71, v24 offset:560
	s_waitcnt vmcnt(20) lgkmcnt(0)
	v_fmac_f32_e32 v34, v192, v36
	v_fmac_f32_e32 v33, v192, v37
	v_fmac_f32_e32 v32, v192, v38
	v_fmac_f32_e32 v31, v192, v39
	v_fmac_f32_e32 v30, v192, v40
	v_fmac_f32_e32 v29, v192, v41
	v_fmac_f32_e32 v28, v192, v42
	v_fmac_f32_e32 v27, v192, v43
	v_fmac_f32_e32 v4, v192, v68
	v_fmac_f32_e32 v34, v193, v44
	v_fmac_f32_e32 v33, v193, v45
	v_fmac_f32_e32 v32, v193, v46
	v_fmac_f32_e32 v31, v193, v47
	v_fmac_f32_e32 v30, v193, v48
	v_fmac_f32_e32 v29, v193, v49
	v_fmac_f32_e32 v28, v193, v50
	v_fmac_f32_e32 v27, v193, v51
	v_fmac_f32_e32 v4, v193, v69
	v_fmac_f32_e32 v34, v194, v52
	v_fmac_f32_e32 v33, v194, v53
	v_fmac_f32_e32 v32, v194, v54
	v_fmac_f32_e32 v31, v194, v55
	v_fmac_f32_e32 v30, v194, v56
	v_fmac_f32_e32 v29, v194, v57
	v_fmac_f32_e32 v28, v194, v58
	v_fmac_f32_e32 v27, v194, v59
	v_fmac_f32_e32 v4, v194, v70
	v_fmac_f32_e32 v34, v195, v60
	v_fmac_f32_e32 v33, v195, v61
	v_fmac_f32_e32 v32, v195, v62
	v_fmac_f32_e32 v31, v195, v63
	v_fmac_f32_e32 v30, v195, v64
	v_fmac_f32_e32 v29, v195, v65
	v_fmac_f32_e32 v28, v195, v66
	v_fmac_f32_e32 v27, v195, v67
	v_fmac_f32_e32 v4, v195, v71
	ds_read_b128 v[36:39], v24 offset:576
	ds_read_b128 v[40:43], v24 offset:592
	ds_read_b32 v68, v24 offset:608
	ds_read_b128 v[44:47], v24 offset:624
	ds_read_b128 v[48:51], v24 offset:640
	ds_read_b32 v69, v24 offset:656
	ds_read_b128 v[52:55], v24 offset:672
	ds_read_b128 v[56:59], v24 offset:688
	ds_read_b32 v70, v24 offset:704
	ds_read_b128 v[60:63], v24 offset:720
	ds_read_b128 v[64:67], v24 offset:736
	ds_read_b32 v71, v24 offset:752
	s_waitcnt vmcnt(16) lgkmcnt(0)
	v_fmac_f32_e32 v34, v196, v36
	v_fmac_f32_e32 v33, v196, v37
	v_fmac_f32_e32 v32, v196, v38
	v_fmac_f32_e32 v31, v196, v39
	v_fmac_f32_e32 v30, v196, v40
	v_fmac_f32_e32 v29, v196, v41
	v_fmac_f32_e32 v28, v196, v42
	v_fmac_f32_e32 v27, v196, v43
	v_fmac_f32_e32 v4, v196, v68
	v_fmac_f32_e32 v34, v197, v44
	v_fmac_f32_e32 v33, v197, v45
	v_fmac_f32_e32 v32, v197, v46
	v_fmac_f32_e32 v31, v197, v47
	v_fmac_f32_e32 v30, v197, v48
	v_fmac_f32_e32 v29, v197, v49
	v_fmac_f32_e32 v28, v197, v50
	v_fmac_f32_e32 v27, v197, v51
	v_fmac_f32_e32 v4, v197, v69
	v_fmac_f32_e32 v34, v198, v52
	v_fmac_f32_e32 v33, v198, v53
	v_fmac_f32_e32 v32, v198, v54
	v_fmac_f32_e32 v31, v198, v55
	v_fmac_f32_e32 v30, v198, v56
	v_fmac_f32_e32 v29, v198, v57
	v_fmac_f32_e32 v28, v198, v58
	v_fmac_f32_e32 v27, v198, v59
	v_fmac_f32_e32 v4, v198, v70
	v_fmac_f32_e32 v34, v199, v60
	v_fmac_f32_e32 v33, v199, v61
	v_fmac_f32_e32 v32, v199, v62
	v_fmac_f32_e32 v31, v199, v63
	v_fmac_f32_e32 v30, v199, v64
	v_fmac_f32_e32 v29, v199, v65
	v_fmac_f32_e32 v28, v199, v66
	v_fmac_f32_e32 v27, v199, v67
	v_fmac_f32_e32 v4, v199, v71
	ds_read_b128 v[36:39], v24 offset:768
	ds_read_b128 v[40:43], v24 offset:784
	ds_read_b32 v68, v24 offset:800
	ds_read_b128 v[44:47], v24 offset:816
	ds_read_b128 v[48:51], v24 offset:832
	ds_read_b32 v69, v24 offset:848
	ds_read_b128 v[52:55], v24 offset:864
	ds_read_b128 v[56:59], v24 offset:880
	ds_read_b32 v70, v24 offset:896
	ds_read_b128 v[60:63], v24 offset:912
	ds_read_b128 v[64:67], v24 offset:928
	ds_read_b32 v71, v24 offset:944
	s_waitcnt vmcnt(12) lgkmcnt(0)
	v_fmac_f32_e32 v34, v200, v36
	v_fmac_f32_e32 v33, v200, v37
	v_fmac_f32_e32 v32, v200, v38
	v_fmac_f32_e32 v31, v200, v39
	v_fmac_f32_e32 v30, v200, v40
	v_fmac_f32_e32 v29, v200, v41
	v_fmac_f32_e32 v28, v200, v42
	v_fmac_f32_e32 v27, v200, v43
	v_fmac_f32_e32 v4, v200, v68
	v_fmac_f32_e32 v34, v201, v44
	v_fmac_f32_e32 v33, v201, v45
	v_fmac_f32_e32 v32, v201, v46
	v_fmac_f32_e32 v31, v201, v47
	v_fmac_f32_e32 v30, v201, v48
	v_fmac_f32_e32 v29, v201, v49
	v_fmac_f32_e32 v28, v201, v50
	v_fmac_f32_e32 v27, v201, v51
	v_fmac_f32_e32 v4, v201, v69
	v_fmac_f32_e32 v34, v202, v52
	v_fmac_f32_e32 v33, v202, v53
	v_fmac_f32_e32 v32, v202, v54
	v_fmac_f32_e32 v31, v202, v55
	v_fmac_f32_e32 v30, v202, v56
	v_fmac_f32_e32 v29, v202, v57
	v_fmac_f32_e32 v28, v202, v58
	v_fmac_f32_e32 v27, v202, v59
	v_fmac_f32_e32 v4, v202, v70
	v_fmac_f32_e32 v34, v203, v60
	v_fmac_f32_e32 v33, v203, v61
	v_fmac_f32_e32 v32, v203, v62
	v_fmac_f32_e32 v31, v203, v63
	v_fmac_f32_e32 v30, v203, v64
	v_fmac_f32_e32 v29, v203, v65
	v_fmac_f32_e32 v28, v203, v66
	v_fmac_f32_e32 v27, v203, v67
	v_fmac_f32_e32 v4, v203, v71
	ds_read_b128 v[36:39], v24 offset:960
	ds_read_b128 v[40:43], v24 offset:976
	ds_read_b32 v68, v24 offset:992
	ds_read_b128 v[44:47], v24 offset:1008
	ds_read_b128 v[48:51], v24 offset:1024
	ds_read_b32 v69, v24 offset:1040
	ds_read_b128 v[52:55], v24 offset:1056
	ds_read_b128 v[56:59], v24 offset:1072
	ds_read_b32 v70, v24 offset:1088
	ds_read_b128 v[60:63], v24 offset:1104
	ds_read_b128 v[64:67], v24 offset:1120
	ds_read_b32 v71, v24 offset:1136
	s_waitcnt vmcnt(8) lgkmcnt(0)
	v_fmac_f32_e32 v34, v204, v36
	v_fmac_f32_e32 v33, v204, v37
	v_fmac_f32_e32 v32, v204, v38
	v_fmac_f32_e32 v31, v204, v39
	v_fmac_f32_e32 v30, v204, v40
	v_fmac_f32_e32 v29, v204, v41
	v_fmac_f32_e32 v28, v204, v42
	v_fmac_f32_e32 v27, v204, v43
	v_fmac_f32_e32 v4, v204, v68
	v_fmac_f32_e32 v34, v205, v44
	v_fmac_f32_e32 v33, v205, v45
	v_fmac_f32_e32 v32, v205, v46
	v_fmac_f32_e32 v31, v205, v47
	v_fmac_f32_e32 v30, v205, v48
	v_fmac_f32_e32 v29, v205, v49
	v_fmac_f32_e32 v28, v205, v50
	v_fmac_f32_e32 v27, v205, v51
	v_fmac_f32_e32 v4, v205, v69
	v_fmac_f32_e32 v34, v206, v52
	v_fmac_f32_e32 v33, v206, v53
	v_fmac_f32_e32 v32, v206, v54
	v_fmac_f32_e32 v31, v206, v55
	v_fmac_f32_e32 v30, v206, v56
	v_fmac_f32_e32 v29, v206, v57
	v_fmac_f32_e32 v28, v206, v58
	v_fmac_f32_e32 v27, v206, v59
	v_fmac_f32_e32 v4, v206, v70
	v_fmac_f32_e32 v34, v207, v60
	v_fmac_f32_e32 v33, v207, v61
	v_fmac_f32_e32 v32, v207, v62
	v_fmac_f32_e32 v31, v207, v63
	v_fmac_f32_e32 v30, v207, v64
	v_fmac_f32_e32 v29, v207, v65
	v_fmac_f32_e32 v28, v207, v66
	v_fmac_f32_e32 v27, v207, v67
	v_fmac_f32_e32 v4, v207, v71
	ds_read_b128 v[36:39], v24 offset:1152
	ds_read_b128 v[40:43], v24 offset:1168
	ds_read_b32 v68, v24 offset:1184
	ds_read_b128 v[44:47], v24 offset:1200
	ds_read_b128 v[48:51], v24 offset:1216
	ds_read_b32 v69, v24 offset:1232
	ds_read_b128 v[52:55], v24 offset:1248
	ds_read_b128 v[56:59], v24 offset:1264
	ds_read_b32 v70, v24 offset:1280
	ds_read_b128 v[60:63], v24 offset:1296
	ds_read_b128 v[64:67], v24 offset:1312
	ds_read_b32 v71, v24 offset:1328
	s_waitcnt vmcnt(4) lgkmcnt(0)
	v_fmac_f32_e32 v34, v208, v36
	v_fmac_f32_e32 v33, v208, v37
	v_fmac_f32_e32 v32, v208, v38
	v_fmac_f32_e32 v31, v208, v39
	v_fmac_f32_e32 v30, v208, v40
	v_fmac_f32_e32 v29, v208, v41
	v_fmac_f32_e32 v28, v208, v42
	v_fmac_f32_e32 v27, v208, v43
	v_fmac_f32_e32 v4, v208, v68
	v_fmac_f32_e32 v34, v209, v44
	v_fmac_f32_e32 v33, v209, v45
	v_fmac_f32_e32 v32, v209, v46
	v_fmac_f32_e32 v31, v209, v47
	v_fmac_f32_e32 v30, v209, v48
	v_fmac_f32_e32 v29, v209, v49
	v_fmac_f32_e32 v28, v209, v50
	v_fmac_f32_e32 v27, v209, v51
	v_fmac_f32_e32 v4, v209, v69
	v_fmac_f32_e32 v34, v210, v52
	v_fmac_f32_e32 v33, v210, v53
	v_fmac_f32_e32 v32, v210, v54
	v_fmac_f32_e32 v31, v210, v55
	v_fmac_f32_e32 v30, v210, v56
	v_fmac_f32_e32 v29, v210, v57
	v_fmac_f32_e32 v28, v210, v58
	v_fmac_f32_e32 v27, v210, v59
	v_fmac_f32_e32 v4, v210, v70
	v_fmac_f32_e32 v34, v211, v60
	v_fmac_f32_e32 v33, v211, v61
	v_fmac_f32_e32 v32, v211, v62
	v_fmac_f32_e32 v31, v211, v63
	v_fmac_f32_e32 v30, v211, v64
	v_fmac_f32_e32 v29, v211, v65
	v_fmac_f32_e32 v28, v211, v66
	v_fmac_f32_e32 v27, v211, v67
	v_fmac_f32_e32 v4, v211, v71
	ds_read_b128 v[36:39], v24 offset:1344
	ds_read_b128 v[40:43], v24 offset:1360
	ds_read_b32 v68, v24 offset:1376
	ds_read_b128 v[44:47], v24 offset:1392
	ds_read_b128 v[48:51], v24 offset:1408
	ds_read_b32 v69, v24 offset:1424
	ds_read_b128 v[52:55], v24 offset:1440
	ds_read_b128 v[56:59], v24 offset:1456
	ds_read_b32 v70, v24 offset:1472
	ds_read_b128 v[60:63], v24 offset:1488
	ds_read_b128 v[64:67], v24 offset:1504
	ds_read_b32 v71, v24 offset:1520
	s_waitcnt vmcnt(0) lgkmcnt(0)
	v_fmac_f32_e32 v34, v212, v36
	v_fmac_f32_e32 v33, v212, v37
	v_fmac_f32_e32 v32, v212, v38
	v_fmac_f32_e32 v31, v212, v39
	v_fmac_f32_e32 v30, v212, v40
	v_fmac_f32_e32 v29, v212, v41
	v_fmac_f32_e32 v28, v212, v42
	v_fmac_f32_e32 v27, v212, v43
	v_fmac_f32_e32 v4, v212, v68
	v_fmac_f32_e32 v34, v213, v44
	v_fmac_f32_e32 v33, v213, v45
	v_fmac_f32_e32 v32, v213, v46
	v_fmac_f32_e32 v31, v213, v47
	v_fmac_f32_e32 v30, v213, v48
	v_fmac_f32_e32 v29, v213, v49
	v_fmac_f32_e32 v28, v213, v50
	v_fmac_f32_e32 v27, v213, v51
	v_fmac_f32_e32 v4, v213, v69
	v_fmac_f32_e32 v34, v214, v52
	v_fmac_f32_e32 v33, v214, v53
	v_fmac_f32_e32 v32, v214, v54
	v_fmac_f32_e32 v31, v214, v55
	v_fmac_f32_e32 v30, v214, v56
	v_fmac_f32_e32 v29, v214, v57
	v_fmac_f32_e32 v28, v214, v58
	v_fmac_f32_e32 v27, v214, v59
	v_fmac_f32_e32 v4, v214, v70
	v_fmac_f32_e32 v34, v215, v60
	v_fmac_f32_e32 v33, v215, v61
	v_fmac_f32_e32 v32, v215, v62
	v_fmac_f32_e32 v31, v215, v63
	v_fmac_f32_e32 v30, v215, v64
	v_fmac_f32_e32 v29, v215, v65
	v_fmac_f32_e32 v28, v215, v66
	v_fmac_f32_e32 v27, v215, v67
	v_fmac_f32_e32 v4, v215, v71
	s_and_saveexec_b64 s[54:55], s[6:7]
	s_cbranch_execz .LBB0_28
	ds_write_b32 v14, v34 offset:6144
	ds_write_b32 v15, v33 offset:6144
	ds_write_b32 v14, v32 offset:8192
	ds_write_b32 v16, v31 offset:6144
	ds_write_b32 v14, v30 offset:10240
	ds_write_b32 v17, v29 offset:6144
	ds_write_b32 v14, v28 offset:12288
	ds_write_b32 v18, v27 offset:6144
	ds_write_b32 v14, v4 offset:14336
